# G0 epilogue: PROJ staging reads issued ahead of the store ladder (5 of 8 reads hoisted into dead accumulator registers)
# baseline (speedup 1.0000x reference)
; DI f32x4 mfma16(bf16x8 a, bf16x8 b, f32x4 c) { return __builtin_amdgcn_mfma_f32_16x16x32_bf16(a, b, c, 0, 0, 0); }
; template <int MODE>
; PH void gemm_phase(const Params& p, int layer) {
;     ...
;           const u16* cX = sX + (g & 1) * 128 * 72;
;           const u16* cW = sW + (g & 1) * 128 * 72;
;           u16* dX = sX + ((g + 1) & 1) * 128 * 72;
;           u16* dW = sW + ((g + 1) & 1) * 128 * 72;
; #pragma unroll
;           for (int ks = 0; ks < 2; ++ks) {
;             bf16x8 wf[4], xf[4];
; #pragma unroll
;             for (int i = 0; i < 4; ++i) {
;               wf[i] = ldfrag(cW, 72, wn * 64 + i * 16, ks * 32, lane);
;               xf[i] = ldfrag(cX, 72, wm * 64 + i * 16, ks * 32, lane);
;             }
;             __builtin_amdgcn_sched_barrier(0);
; #pragma unroll
;             for (int nt = 0; nt < 4; ++nt) {
; #pragma unroll
;               for (int mt = 0; mt < 4; ++mt) acc[nt][mt] = mfma16(wf[nt], xf[mt], acc[nt][mt]);
;               if (ks == 0) *(u32x4*)(dX + soff + nt * 32 * 72) = rx[(s + 1) & 1][nt];
;               else         *(u32x4*)(dW + soff + nt * 32 * 72) = rw[(s + 1) & 1][nt];
;               __builtin_amdgcn_sched_barrier(0);
;             }
;             if (ks == 0) { GLOAD(s, g + 2); __builtin_amdgcn_sched_barrier(0); }
;           }
.LBB0_175:
	s_add_i32 s13, s25, -1
	v_readlane_b32 s45, v254, 57
	s_min_i32 s2, s13, s45
	s_ashr_i32 s6, s2, 4
	s_mul_i32 s6, s6, s64
	v_readlane_b32 s44, v255, 8
	s_waitcnt vmcnt(9)
	ds_read_b128 v[96:99], v233 offset:36864
	s_waitcnt vmcnt(7)
	ds_read_b128 v[100:103], v233 offset:38912
	s_waitcnt vmcnt(3)
	ds_read_b128 v[104:107], v234
	ds_read_b128 v[108:111], v234 offset:2048
	s_waitcnt vmcnt(1)
	ds_read_b128 v[112:115], v233 offset:40960
	ds_read_b128 v[116:119], v233 offset:43008
	ds_read_b128 v[120:123], v234 offset:4096
	ds_read_b128 v[124:127], v234 offset:6144
	s_add_i32 s6, s6, s44
	s_mul_hi_i32 s22, s6, 0xd20d20d3
	s_add_i32 s22, s22, s6
	s_lshr_b32 s42, s22, 31
	s_ashr_i32 s22, s22, 8
	s_add_i32 s22, s22, s42
	s_mul_i32 s42, s22, 0x138
	s_sub_i32 s42, s6, s42
	s_lshr_b32 s43, s42, 3
	s_lshl_b32 s42, s42, 7
	s_lshl_b32 s22, s22, 10
	s_and_b32 s42, s42, 0x380
	s_lshl_b32 s2, s2, 7
	s_add_i32 s7, s6, 0xffffec80
	s_or_b32 s22, s42, s22
	s_and_b32 s2, s2, 0x780
	s_cmpk_lt_i32 s6, 0x1380
	s_cselect_b32 s76, s22, 0x4000
	s_cselect_b32 s78, s43, s7
	s_lshl_b32 s76, s76, 11
	s_lshl_b32 s78, s78, 18
	s_add_i32 s76, s76, s2
	s_add_i32 s78, s78, s2
	s_add_u32 s76, s72, s76
	s_addc_u32 s77, s73, 0
	s_add_u32 s78, s74, s78
	s_addc_u32 s79, s75, 0
	s_waitcnt lgkmcnt(5)
	v_mfma_f32_16x16x32_bf16 v[92:95], v[96:99], v[104:107], v[92:95]
	s_waitcnt vmcnt(7)
	ds_write_b128 v203, v[16:19] offset:18432
	s_waitcnt lgkmcnt(5)
	v_mfma_f32_16x16x32_bf16 v[88:91], v[96:99], v[108:111], v[88:91]
	s_waitcnt lgkmcnt(2)
	v_mfma_f32_16x16x32_bf16 v[84:87], v[96:99], v[120:123], v[84:87]
	s_waitcnt lgkmcnt(1)
	v_mfma_f32_16x16x32_bf16 v[16:19], v[96:99], v[124:127], v[80:83]
	v_mfma_f32_16x16x32_bf16 v[76:79], v[100:103], v[104:107], v[76:79]
	s_waitcnt vmcnt(5)
	ds_write_b128 v203, v[20:23] offset:22528
	v_mfma_f32_16x16x32_bf16 v[72:75], v[100:103], v[108:111], v[72:75]
	v_mfma_f32_16x16x32_bf16 v[68:71], v[100:103], v[120:123], v[68:71]
	v_mfma_f32_16x16x32_bf16 v[20:23], v[100:103], v[124:127], v[64:67]
	v_mfma_f32_16x16x32_bf16 v[60:63], v[112:115], v[104:107], v[60:63]
	s_waitcnt vmcnt(3)
	ds_write_b128 v203, v[24:27] offset:26624
	v_mfma_f32_16x16x32_bf16 v[56:59], v[112:115], v[108:111], v[56:59]
	v_mfma_f32_16x16x32_bf16 v[52:55], v[112:115], v[120:123], v[52:55]
	v_mfma_f32_16x16x32_bf16 v[24:27], v[112:115], v[124:127], v[48:51]
	v_mfma_f32_16x16x32_bf16 v[44:47], v[116:119], v[104:107], v[44:47]
	s_waitcnt vmcnt(1)
	ds_write_b128 v203, v[28:31] offset:30720
	v_mfma_f32_16x16x32_bf16 v[40:43], v[116:119], v[108:111], v[40:43]
	v_mfma_f32_16x16x32_bf16 v[36:39], v[116:119], v[120:123], v[36:39]
	v_mfma_f32_16x16x32_bf16 v[28:31], v[116:119], v[124:127], v[32:35]
	ds_read_b128 v[112:115], v240 offset:36864
	ds_read_b128 v[116:119], v240 offset:38912
	ds_read_b128 v[120:123], v241
	ds_read_b128 v[124:127], v241 offset:2048
	ds_read_b128 v[128:131], v240 offset:40960
	s_waitcnt vmcnt(8)
	ds_read_b128 v[132:135], v240 offset:43008
	ds_read_b128 v[136:139], v241 offset:4096
	ds_read_b128 v[146:149], v241 offset:6144
	global_load_dwordx4 v[32:35], v242, s[76:77]
	global_load_dwordx4 v[48:51], v242, s[78:79]
	global_load_dwordx4 v[64:67], v243, s[76:77]
	global_load_dwordx4 v[96:99], v243, s[78:79]
	global_load_dwordx4 v[80:83], v244, s[76:77]
	global_load_dwordx4 v[100:103], v244, s[78:79]
	global_load_dwordx4 v[104:107], v245, s[76:77]
	global_load_dwordx4 v[108:111], v245, s[78:79]
	s_waitcnt lgkmcnt(5)
	v_mfma_f32_16x16x32_bf16 v[92:95], v[112:115], v[120:123], v[92:95]
	ds_write_b128 v203, v[0:3] offset:55296
	s_waitcnt lgkmcnt(5)
	v_mfma_f32_16x16x32_bf16 v[88:91], v[112:115], v[124:127], v[88:91]
	s_waitcnt lgkmcnt(2)
	v_mfma_f32_16x16x32_bf16 v[84:87], v[112:115], v[136:139], v[84:87]
	s_waitcnt lgkmcnt(1)
	v_mfma_f32_16x16x32_bf16 v[0:3], v[112:115], v[146:149], v[16:19]
	v_mfma_f32_16x16x32_bf16 v[16:19], v[116:119], v[120:123], v[76:79]
	ds_write_b128 v203, v[4:7] offset:59392
	v_mfma_f32_16x16x32_bf16 v[72:75], v[116:119], v[124:127], v[72:75]
	v_mfma_f32_16x16x32_bf16 v[68:71], v[116:119], v[136:139], v[68:71]
	v_mfma_f32_16x16x32_bf16 v[4:7], v[116:119], v[146:149], v[20:23]
	v_mfma_f32_16x16x32_bf16 v[20:23], v[128:131], v[120:123], v[60:63]
	ds_write_b128 v203, v[8:11] offset:63488
	v_mfma_f32_16x16x32_bf16 v[56:59], v[128:131], v[124:127], v[56:59]
	v_mfma_f32_16x16x32_bf16 v[52:55], v[128:131], v[136:139], v[52:55]
	v_mfma_f32_16x16x32_bf16 v[8:11], v[128:131], v[146:149], v[24:27]
	v_mfma_f32_16x16x32_bf16 v[24:27], v[132:135], v[120:123], v[44:47]
	s_waitcnt vmcnt(8)
	ds_write_b128 v204, v[12:15] offset:30720
	v_mfma_f32_16x16x32_bf16 v[40:43], v[132:135], v[124:127], v[40:43]
	v_mfma_f32_16x16x32_bf16 v[36:39], v[132:135], v[136:139], v[36:39]
	v_mfma_f32_16x16x32_bf16 v[12:15], v[132:135], v[146:149], v[28:31]
	s_min_i32 s2, s25, s45
	s_ashr_i32 s6, s2, 4
	s_waitcnt lgkmcnt(0)
	s_barrier
; DI f32x4 mfma16(bf16x8 a, bf16x8 b, f32x4 c) { return __builtin_amdgcn_mfma_f32_16x16x32_bf16(a, b, c, 0, 0, 0); }
; template <int MODE>
; PH void gemm_phase(const Params& p, int layer) {
;     ...
;           const u16* cX = sX + (g & 1) * 128 * 72;
;           const u16* cW = sW + (g & 1) * 128 * 72;
;           u16* dX = sX + ((g + 1) & 1) * 128 * 72;
;           u16* dW = sW + ((g + 1) & 1) * 128 * 72;
; #pragma unroll
;           for (int ks = 0; ks < 2; ++ks) {
;             bf16x8 wf[4], xf[4];
; #pragma unroll
;             for (int i = 0; i < 4; ++i) {
;               wf[i] = ldfrag(cW, 72, wn * 64 + i * 16, ks * 32, lane);
;               xf[i] = ldfrag(cX, 72, wm * 64 + i * 16, ks * 32, lane);
;             }
;             __builtin_amdgcn_sched_barrier(0);
; #pragma unroll
;             for (int nt = 0; nt < 4; ++nt) {
; #pragma unroll
;               for (int mt = 0; mt < 4; ++mt) acc[nt][mt] = mfma16(wf[nt], xf[mt], acc[nt][mt]);
;               if (ks == 0) *(u32x4*)(dX + soff + nt * 32 * 72) = rx[(s + 1) & 1][nt];
;               else         *(u32x4*)(dW + soff + nt * 32 * 72) = rw[(s + 1) & 1][nt];
;               __builtin_amdgcn_sched_barrier(0);
;             }
;             if (ks == 0) { GLOAD(s, g + 2); __builtin_amdgcn_sched_barrier(0); }
;           }
;           __syncthreads();
	s_mul_i32 s6, s6, s64
	ds_read_b128 v[28:31], v233 offset:55296
	ds_read_b128 v[44:47], v233 offset:57344
	ds_read_b128 v[60:63], v234 offset:18432
	ds_read_b128 v[76:79], v234 offset:20480
	ds_read_b128 v[112:115], v233 offset:59392
	ds_read_b128 v[116:119], v233 offset:61440
	ds_read_b128 v[120:123], v234 offset:22528
	ds_read_b128 v[124:127], v234 offset:24576
	s_add_i32 s6, s6, s44
	s_mul_hi_i32 s22, s6, 0xd20d20d3
	s_add_i32 s22, s22, s6
	s_lshr_b32 s42, s22, 31
	s_ashr_i32 s22, s22, 8
	s_add_i32 s22, s22, s42
	s_mul_i32 s42, s22, 0x138
	s_sub_i32 s42, s6, s42
	s_lshr_b32 s43, s42, 3
	s_lshl_b32 s42, s42, 7
	s_lshl_b32 s22, s22, 10
	s_and_b32 s42, s42, 0x380
	s_lshl_b32 s2, s2, 7
	s_add_i32 s7, s6, 0xffffec80
	s_or_b32 s22, s42, s22
	s_and_b32 s2, s2, 0x780
	s_cmpk_lt_i32 s6, 0x1380
	s_cselect_b32 s76, s22, 0x4000
	s_cselect_b32 s78, s43, s7
	s_lshl_b32 s76, s76, 11
	s_lshl_b32 s78, s78, 18
	s_add_i32 s76, s76, s2
	s_add_i32 s78, s78, s2
	s_add_u32 s76, s72, s76
	s_addc_u32 s77, s73, 0
	s_add_u32 s78, s74, s78
	s_addc_u32 s79, s75, 0
	s_waitcnt lgkmcnt(5)
	v_mfma_f32_16x16x32_bf16 v[92:95], v[28:31], v[60:63], v[92:95]
	s_waitcnt vmcnt(7)
	ds_write_b128 v203, v[32:35]
	s_waitcnt lgkmcnt(5)
	v_mfma_f32_16x16x32_bf16 v[88:91], v[28:31], v[76:79], v[88:91]
	s_waitcnt lgkmcnt(2)
	v_mfma_f32_16x16x32_bf16 v[84:87], v[28:31], v[120:123], v[84:87]
	s_waitcnt lgkmcnt(1)
	v_mfma_f32_16x16x32_bf16 v[32:35], v[28:31], v[124:127], v[0:3]
	v_mfma_f32_16x16x32_bf16 v[128:131], v[44:47], v[60:63], v[16:19]
	s_waitcnt vmcnt(5)
	ds_write_b128 v203, v[64:67] offset:4096
	v_mfma_f32_16x16x32_bf16 v[72:75], v[44:47], v[76:79], v[72:75]
	v_mfma_f32_16x16x32_bf16 v[68:71], v[44:47], v[120:123], v[68:71]
	v_mfma_f32_16x16x32_bf16 v[44:47], v[44:47], v[124:127], v[4:7]
	v_mfma_f32_16x16x32_bf16 v[56:59], v[112:115], v[76:79], v[56:59]
	s_waitcnt vmcnt(3)
	ds_write_b128 v203, v[80:83] offset:8192
	v_mfma_f32_16x16x32_bf16 v[52:55], v[112:115], v[120:123], v[52:55]
	v_mfma_f32_16x16x32_bf16 v[132:135], v[112:115], v[60:63], v[20:23]
	v_mfma_f32_16x16x32_bf16 v[112:115], v[112:115], v[124:127], v[8:11]
	v_mfma_f32_16x16x32_bf16 v[40:43], v[116:119], v[76:79], v[40:43]
	s_waitcnt vmcnt(1)
	ds_write_b128 v203, v[104:107] offset:12288
	v_mfma_f32_16x16x32_bf16 v[36:39], v[116:119], v[120:123], v[36:39]
	v_mfma_f32_16x16x32_bf16 v[136:139], v[116:119], v[60:63], v[24:27]
	v_mfma_f32_16x16x32_bf16 v[104:107], v[116:119], v[124:127], v[12:15]
	ds_read_b128 v[60:63], v240 offset:55296
	ds_read_b128 v[64:67], v240 offset:57344
	ds_read_b128 v[116:119], v241 offset:18432
	ds_read_b128 v[120:123], v241 offset:20480
	ds_read_b128 v[124:127], v240 offset:59392
	ds_read_b128 v[146:149], v240 offset:61440
	ds_read_b128 v[150:153], v241 offset:22528
	ds_read_b128 v[154:157], v241 offset:24576
	global_load_dwordx4 v[16:19], v242, s[76:77]
	global_load_dwordx4 v[0:3], v242, s[78:79]
	global_load_dwordx4 v[20:23], v243, s[76:77]
	global_load_dwordx4 v[4:7], v243, s[78:79]
	global_load_dwordx4 v[24:27], v244, s[76:77]
	global_load_dwordx4 v[8:11], v244, s[78:79]
	global_load_dwordx4 v[28:31], v245, s[76:77]
	global_load_dwordx4 v[12:15], v245, s[78:79]
	s_waitcnt lgkmcnt(5)
	v_mfma_f32_16x16x32_bf16 v[92:95], v[60:63], v[116:119], v[92:95]
	ds_write_b128 v203, v[48:51] offset:36864
	s_waitcnt lgkmcnt(5)
	v_mfma_f32_16x16x32_bf16 v[88:91], v[60:63], v[120:123], v[88:91]
	s_waitcnt lgkmcnt(2)
	v_mfma_f32_16x16x32_bf16 v[84:87], v[60:63], v[150:153], v[84:87]
	s_waitcnt lgkmcnt(1)
	v_mfma_f32_16x16x32_bf16 v[80:83], v[60:63], v[154:157], v[32:35]
	v_mfma_f32_16x16x32_bf16 v[76:79], v[64:67], v[116:119], v[128:131]
	ds_write_b128 v203, v[96:99] offset:40960
	v_mfma_f32_16x16x32_bf16 v[72:75], v[64:67], v[120:123], v[72:75]
	v_mfma_f32_16x16x32_bf16 v[68:71], v[64:67], v[150:153], v[68:71]
	v_mfma_f32_16x16x32_bf16 v[64:67], v[64:67], v[154:157], v[44:47]
	v_mfma_f32_16x16x32_bf16 v[60:63], v[124:127], v[116:119], v[132:135]
	ds_write_b128 v203, v[100:103] offset:45056
	v_mfma_f32_16x16x32_bf16 v[56:59], v[124:127], v[120:123], v[56:59]
	v_mfma_f32_16x16x32_bf16 v[52:55], v[124:127], v[150:153], v[52:55]
	v_mfma_f32_16x16x32_bf16 v[48:51], v[124:127], v[154:157], v[112:115]
	v_mfma_f32_16x16x32_bf16 v[44:47], v[146:149], v[116:119], v[136:139]
	s_waitcnt vmcnt(8)
	ds_write_b128 v203, v[108:111] offset:49152
	v_mfma_f32_16x16x32_bf16 v[40:43], v[146:149], v[120:123], v[40:43]
	v_mfma_f32_16x16x32_bf16 v[36:39], v[146:149], v[150:153], v[36:39]
	v_mfma_f32_16x16x32_bf16 v[32:35], v[146:149], v[154:157], v[104:107]
	s_cmp_lg_u32 s1, 14
	s_waitcnt lgkmcnt(0)
	s_barrier
	s_cbranch_scc1 .LBB0_172
; template <int MODE>
; PH void gemm_phase(const Params& p, int layer) {
;     ...
; #pragma unroll
;               for (int i = 0; i < 8; ++i) {
;                 const int row = (tid >> 4) + 16 * i, ch = tid & 15;
;                 const u16* eb = (row < 64 ? eX + row * 136 : eW + (row - 64) * 136) + ch * 8;
;                 *(u32x4*)(PROJ + (size_t)(m0 + row) * NPAD + n0 + ch * 8) = *(const u32x4*)eb;
;               }
	s_lshr_b32 s0, s0, 4
	s_mul_i32 s0, s0, s64
	v_readlane_b32 s1, v255, 8
	s_add_i32 s0, s0, s1
	s_mul_hi_i32 s2, s0, 0xd20d20d3
	s_add_i32 s2, s2, s0
	s_lshr_b32 s6, s2, 31
	s_ashr_i32 s2, s2, 8
	v_cvt_pk_bf16_f32 v96, v92, v93
	v_cvt_pk_bf16_f32 v97, v94, v95
	v_cvt_pk_bf16_f32 v98, v76, v77
	v_cvt_pk_bf16_f32 v99, v78, v79
	s_add_i32 s2, s2, s6
	ds_write2_b64 v235, v[96:97], v[98:99] offset1:4
	v_cvt_pk_bf16_f32 v96, v60, v61
	v_cvt_pk_bf16_f32 v97, v62, v63
	v_cvt_pk_bf16_f32 v98, v44, v45
	v_cvt_pk_bf16_f32 v99, v46, v47
	s_mul_i32 s6, s2, 0x138
	ds_write2_b64 v235, v[96:97], v[98:99] offset0:8 offset1:12
	v_cvt_pk_bf16_f32 v96, v88, v89
	v_cvt_pk_bf16_f32 v97, v90, v91
	v_cvt_pk_bf16_f32 v98, v72, v73
	v_cvt_pk_bf16_f32 v99, v74, v75
	v_add_u32_e32 v100, 0x1000, v235
	s_sub_i32 s6, s0, s6
	ds_write2_b64 v100, v[96:97], v[98:99] offset0:32 offset1:36
	v_cvt_pk_bf16_f32 v96, v56, v57
	v_cvt_pk_bf16_f32 v97, v58, v59
	v_cvt_pk_bf16_f32 v98, v40, v41
	v_cvt_pk_bf16_f32 v99, v42, v43
	s_ashr_i32 s7, s6, 3
	s_lshl_b32 s6, s6, 7
	ds_write2_b64 v100, v[96:97], v[98:99] offset0:40 offset1:44
	v_cvt_pk_bf16_f32 v96, v84, v85
	v_cvt_pk_bf16_f32 v97, v86, v87
	v_cvt_pk_bf16_f32 v98, v68, v69
	v_cvt_pk_bf16_f32 v99, v70, v71
	v_add_u32_e32 v100, 0x2000, v235
	s_lshl_b32 s2, s2, 10
	s_and_b32 s6, s6, 0x380
	ds_write2_b64 v100, v[96:97], v[98:99] offset0:64 offset1:68
	v_cvt_pk_bf16_f32 v96, v52, v53
	v_cvt_pk_bf16_f32 v97, v54, v55
	v_cvt_pk_bf16_f32 v98, v36, v37
	v_cvt_pk_bf16_f32 v99, v38, v39
	s_add_i32 s1, s0, 0xffffec80
	s_or_b32 s2, s6, s2
	ds_write2_b64 v100, v[96:97], v[98:99] offset0:72 offset1:76
	v_cvt_pk_bf16_f32 v96, v80, v81
	v_cvt_pk_bf16_f32 v97, v82, v83
	v_cvt_pk_bf16_f32 v98, v64, v65
	v_cvt_pk_bf16_f32 v99, v66, v67
	v_add_u32_e32 v100, 0x3000, v235
	s_cmpk_lt_i32 s0, 0x1380
	ds_write2_b64 v100, v[96:97], v[98:99] offset0:96 offset1:100
	v_cvt_pk_bf16_f32 v96, v48, v49
	v_cvt_pk_bf16_f32 v97, v50, v51
	v_cvt_pk_bf16_f32 v98, v32, v33
	v_cvt_pk_bf16_f32 v99, v34, v35
	s_cselect_b32 s44, s7, s1
	ds_write2_b64 v100, v[96:97], v[98:99] offset0:104 offset1:108
	s_waitcnt lgkmcnt(0)
	s_barrier
	ds_read_b128 v[96:99], v218
	ds_read_b128 v[32:35], v219
	ds_read_b128 v[36:39], v220
	ds_read_b128 v[40:43], v221
	ds_read_b128 v[44:47], v222
	ds_read_b128 v[48:51], v223
	s_cselect_b32 s22, s2, 0x4000
	s_lshl_b32 s0, s44, 7
	s_ashr_i32 s1, s0, 31
	v_lshl_add_u64 v[100:101], s[0:1], 1, v[144:145]
	v_add_u32_e32 v104, s22, v205
	v_mad_i64_i32 v[102:103], s[6:7], v104, s97, v[100:101]
	s_waitcnt lgkmcnt(5)
	global_store_dwordx4 v[102:103], v[96:99], off
	v_add_u32_e32 v102, 16, v104
	v_mad_i64_i32 v[102:103], s[6:7], v102, s97, v[100:101]
	s_add_i32 s1, s44, -10
	s_waitcnt lgkmcnt(4)
	global_store_dwordx4 v[102:103], v[32:35], off
	v_add_u32_e32 v102, 32, v104
	v_mad_i64_i32 v[102:103], s[6:7], v102, s97, v[100:101]
	s_cmp_lt_u32 s1, 6
	s_waitcnt lgkmcnt(3)
	global_store_dwordx4 v[102:103], v[36:39], off
	v_add_u32_e32 v102, 48, v104
	v_mad_i64_i32 v[102:103], s[6:7], v102, s97, v[100:101]
	s_cselect_b64 s[42:43], -1, 0
	s_waitcnt lgkmcnt(2)
	global_store_dwordx4 v[102:103], v[40:43], off
	v_add_u32_e32 v102, 64, v104
	v_mad_i64_i32 v[102:103], s[6:7], v102, s97, v[100:101]
	s_cmp_gt_u32 s1, 5
	s_waitcnt lgkmcnt(1)
	global_store_dwordx4 v[102:103], v[44:47], off
	v_add_u32_e32 v102, 0x50, v104
	v_mad_i64_i32 v[102:103], s[6:7], v102, s97, v[100:101]
	s_waitcnt lgkmcnt(0)
	global_store_dwordx4 v[102:103], v[48:51], off
	ds_read_b128 v[96:99], v224
	v_add_u32_e32 v102, 0x60, v104
	v_mad_i64_i32 v[102:103], s[6:7], v102, s97, v[100:101]
	s_waitcnt lgkmcnt(0)
	global_store_dwordx4 v[102:103], v[96:99], off
	v_add_u32_e32 v102, 0x70, v104
	v_mad_i64_i32 v[100:101], s[6:7], v102, s97, v[100:101]
	s_cselect_b64 s[6:7], -1, 0
	s_sub_i32 s1, s44, 28
	s_cmp_gt_u32 s1, 9
	s_cselect_b64 s[44:45], -1, 0
	ds_read_b128 v[96:99], v225
	s_and_b64 s[6:7], s[6:7], s[44:45]
	s_cmpk_gt_i32 s22, 0x3fff
	s_cselect_b64 s[44:45], -1, 0
	s_or_b64 s[6:7], s[6:7], s[44:45]
	s_and_b64 vcc, exec, s[6:7]
	s_waitcnt lgkmcnt(0)
	global_store_dwordx4 v[100:101], v[96:99], off
	s_cbranch_vccnz .LBB0_171
; template <int MODE>
; PH void gemm_phase(const Params& p, int layer) {
;     ...
;                   const int o = tid & 15, rbase = (tid >> 4) * 8;
;                   const int nch = is_lru ? 768 : 1280;
;                   const int chn = (is_lru ? (n0 - C_XL) : (n0 - C_XBC)) + o * 8;
;                   const float* cw = (is_lru ? (p.in[11] + layer * 4 * 768) : (p.in[18] + layer * 4 * 1280)) + chn;
;                   const float* cb = (is_lru ? (p.in[12] + layer * 768) : (p.in[19] + layer * 1280)) + chn;
;                   u16* dst = (u16*)(p.ws + (is_lru ? WS_XL : WS_XBC)) + chn;
;                   float w0[8], w1[8], w2[8], w3[8], bs[8];
; #pragma unroll
;                   for (int h = 0; h < 2; ++h) {
;                     const float4 a0 = *(const float4*)(cw + 0 * nch + 4 * h), a1 = *(const float4*)(cw + 1 * nch + 4 * h);
;                     const float4 a2 = *(const float4*)(cw + 2 * nch + 4 * h), a3 = *(const float4*)(cw + 3 * nch + 4 * h);
;                     const float4 b4 = *(const float4*)(cb + 4 * h);
;                     w0[4 * h] = a0.x; w0[4 * h + 1] = a0.y; w0[4 * h + 2] = a0.z; w0[4 * h + 3] = a0.w;
;                     w1[4 * h] = a1.x; w1[4 * h + 1] = a1.y; w1[4 * h + 2] = a1.z; w1[4 * h + 3] = a1.w;
;                     w2[4 * h] = a2.x; w2[4 * h + 1] = a2.y; w2[4 * h + 2] = a2.z; w2[4 * h + 3] = a2.w;
;                     w3[4 * h] = a3.x; w3[4 * h + 1] = a3.y; w3[4 * h + 2] = a3.z; w3[4 * h + 3] = a3.w;
;                     bs[4 * h] = b4.x; bs[4 * h + 1] = b4.y; bs[4 * h + 2] = b4.z; bs[4 * h + 3] = b4.w;
;                   }
;                   float xa[8], xb[8], xc[8], xd[8], yv[8];
; #pragma unroll
;                   for (int c = 0; c < 8; ++c) { xa[c] = 0.f; xb[c] = 0.f; xc[c] = 0.f; }
;                   if (rbase >= 8) {
;                     const int r1 = rbase - 3, r2 = rbase - 2, r3 = rbase - 1;
;                     unpack8(*(const uint4*)((r1 < 64 ? eX + r1 * 136 : eW + (r1 - 64) * 136) + o * 8), xa);
;                     unpack8(*(const uint4*)((r2 < 64 ? eX + r2 * 136 : eW + (r2 - 64) * 136) + o * 8), xb);
;                     unpack8(*(const uint4*)((r3 < 64 ? eX + r3 * 136 : eW + (r3 - 64) * 136) + o * 8), xc);
;                   }
	s_and_b64 s[6:7], s[42:43], exec
	s_movk_i32 s1, 0x300
	s_cselect_b32 s44, s1, 0x500
	s_movk_i32 s1, 0xfb00
	s_cselect_b32 s1, s1, 0xfffff200
	s_add_i32 s1, s1, s0
	v_or_b32_e32 v146, s1, v206
	s_and_b64 s[0:1], s[42:43], exec
	v_ashrrev_i32_e32 v147, 31, v146
	s_cselect_b32 s1, s9, s18
	s_cselect_b32 s0, s8, s15
	v_lshlrev_b64 v[96:97], 2, v[146:147]
	v_lshl_add_u64 v[100:101], s[0:1], 0, v[96:97]
	s_cselect_b32 s1, s21, s24
	s_cselect_b32 s0, s19, s23
	s_lshl_b32 s2, s44, 2
	v_lshl_add_u64 v[104:105], v[100:101], 0, s[2:3]
	s_lshl_b32 s2, s44, 3
	v_lshl_add_u64 v[106:107], v[100:101], 0, s[2:3]
	s_mul_i32 s2, s44, 12
	v_lshl_add_u64 v[132:133], s[0:1], 0, v[96:97]
	v_lshl_add_u64 v[112:113], v[100:101], 0, s[2:3]
	global_load_dwordx4 v[96:99], v[100:101], off offset:16
	global_load_dwordx4 v[116:119], v[100:101], off
	s_nop 0
	global_load_dwordx4 v[100:103], v[104:105], off offset:16
	global_load_dwordx4 v[120:123], v[104:105], off
	global_load_dwordx4 v[108:111], v[106:107], off offset:16
	global_load_dwordx4 v[128:131], v[106:107], off
	s_nop 0
	global_load_dwordx4 v[104:107], v[112:113], off offset:16
	global_load_dwordx4 v[124:127], v[112:113], off
	s_nop 0
	global_load_dwordx4 v[112:115], v[132:133], off offset:16
	s_nop 0
	global_load_dwordx4 v[132:135], v[132:133], off
	v_mov_b32_e32 v180, 0
	v_mov_b32_e32 v181, v180
	v_mov_b32_e32 v172, v180
	v_mov_b32_e32 v173, v180
	v_mov_b32_e32 v164, v180
	v_mov_b32_e32 v165, v180
	v_mov_b32_e32 v152, v180
	v_mov_b32_e32 v153, v180
	v_mov_b32_e32 v174, v180
	v_mov_b32_e32 v175, v180
	v_mov_b32_e32 v168, v180
	v_mov_b32_e32 v169, v180
	v_mov_b32_e32 v156, v180
	v_mov_b32_e32 v157, v180
	v_mov_b32_e32 v148, v180
	v_mov_b32_e32 v149, v180
	v_mov_b32_e32 v150, v180
	v_mov_b32_e32 v151, v180
	v_mov_b32_e32 v158, v180
	v_mov_b32_e32 v159, v180
	v_mov_b32_e32 v170, v180
	v_mov_b32_e32 v171, v180
	v_mov_b32_e32 v178, v180
	v_mov_b32_e32 v179, v180
	s_and_saveexec_b64 s[0:1], s[36:37]
	s_cbranch_execz .LBB0_179
	ds_read_b128 v[136:139], v208
	ds_read_b128 v[152:155], v209
	s_waitcnt lgkmcnt(1)
	v_lshlrev_b32_e32 v178, 16, v136
	v_and_b32_e32 v179, 0xffff0000, v136
	v_lshlrev_b32_e32 v170, 16, v137
	v_and_b32_e32 v171, 0xffff0000, v137
	v_lshlrev_b32_e32 v158, 16, v138
	v_and_b32_e32 v159, 0xffff0000, v138
	v_lshlrev_b32_e32 v150, 16, v139
	v_and_b32_e32 v151, 0xffff0000, v139
	ds_read_b128 v[136:139], v210
	s_waitcnt lgkmcnt(1)
	v_lshlrev_b32_e32 v174, 16, v152
	v_and_b32_e32 v175, 0xffff0000, v152
	v_lshlrev_b32_e32 v168, 16, v153
	v_and_b32_e32 v169, 0xffff0000, v153
	v_lshlrev_b32_e32 v156, 16, v154
	v_and_b32_e32 v157, 0xffff0000, v154
	v_lshlrev_b32_e32 v148, 16, v155
	v_and_b32_e32 v149, 0xffff0000, v155
	s_waitcnt lgkmcnt(0)
	v_lshlrev_b32_e32 v180, 16, v136
	v_and_b32_e32 v181, 0xffff0000, v136
	v_lshlrev_b32_e32 v172, 16, v137
	v_and_b32_e32 v173, 0xffff0000, v137
	v_lshlrev_b32_e32 v164, 16, v138
	v_and_b32_e32 v165, 0xffff0000, v138
	v_lshlrev_b32_e32 v152, 16, v139
	v_and_b32_e32 v153, 0xffff0000, v139
